# rowwise phases: non-temporal hint on the streamed row loads and the f32 residual stores
# speedup vs baseline: 1.0027x; 1.0027x over previous
; __device__ __forceinline__ void unpack8(u32x4 v, f32x4& a, f32x4& b) { a[0] = bflo(v.x); a[1] = bfhi(v.x); a[2] = bflo(v.y); a[3] = bfhi(v.y); b[0] = bflo(v.z); b[1] = bfhi(v.z); b[2] = bflo(v.w); b[3] = bfhi(v.w); }
; __device__ __forceinline__ void rowwise_row(const bf16_t* frow, const float* hin, float coef, const float* gpost, float* hout, const float* gpre, bf16_t* xn, int lane) {
;     f32x4 f[4][2], h[4][2]; float ss = 0.f;
; #pragma unroll
;     for (int j = 0; j < 4; ++j) { unpack8(*(const u32x4*)(frow + 512 * j + 8 * lane), f[j][0], f[j][1]);
; #pragma unroll
;         for (int i = 0; i < 4; ++i) ss += f[j][0][i] * f[j][0][i] + f[j][1][i] * f[j][1][i]; }
;     const float rs = coef * __frsqrt_rn(wave_sum(ss) * (1.f / DM) + EPS); float s2 = 0.f;
.Lrow_top_p3:
	global_load_dwordx4 v[0:3], v16, s[4:5] offset:0 nt
	global_load_dwordx4 v[4:7], v16, s[4:5] offset:1024 nt
	global_load_dwordx4 v[8:11], v16, s[4:5] offset:2048 nt
	global_load_dwordx4 v[12:15], v16, s[4:5] offset:3072 nt
	global_load_dwordx4 v[56:59], v17, s[8:9] offset:0 nt
	global_load_dwordx4 v[60:63], v17, s[8:9] offset:16 nt
	global_load_dwordx4 v[64:67], v17, s[8:9] offset:2048 nt
	global_load_dwordx4 v[68:71], v17, s[8:9] offset:2064 nt
	global_load_dwordx4 v[72:75], v18, s[8:9] offset:0 nt
	global_load_dwordx4 v[76:79], v18, s[8:9] offset:16 nt
	global_load_dwordx4 v[80:83], v18, s[8:9] offset:2048 nt
	global_load_dwordx4 v[84:87], v18, s[8:9] offset:2064 nt
	s_waitcnt vmcnt(8)
	v_lshlrev_b32_e32 v88, 16, v0
	v_and_b32_e32 v89, 0xffff0000, v0
	v_lshlrev_b32_e32 v90, 16, v1
	v_and_b32_e32 v91, 0xffff0000, v1
	v_lshlrev_b32_e32 v92, 16, v2
	v_and_b32_e32 v93, 0xffff0000, v2
	v_lshlrev_b32_e32 v94, 16, v3
	v_and_b32_e32 v95, 0xffff0000, v3
	v_lshlrev_b32_e32 v96, 16, v4
	v_and_b32_e32 v97, 0xffff0000, v4
	v_lshlrev_b32_e32 v98, 16, v5
	v_and_b32_e32 v99, 0xffff0000, v5
	v_lshlrev_b32_e32 v100, 16, v6
	v_and_b32_e32 v101, 0xffff0000, v6
	v_lshlrev_b32_e32 v102, 16, v7
	v_and_b32_e32 v103, 0xffff0000, v7
	v_lshlrev_b32_e32 v104, 16, v8
	v_and_b32_e32 v105, 0xffff0000, v8
	v_lshlrev_b32_e32 v106, 16, v9
	v_and_b32_e32 v107, 0xffff0000, v9
	v_lshlrev_b32_e32 v108, 16, v10
	v_and_b32_e32 v109, 0xffff0000, v10
	v_lshlrev_b32_e32 v110, 16, v11
	v_and_b32_e32 v111, 0xffff0000, v11
	v_lshlrev_b32_e32 v112, 16, v12
	v_and_b32_e32 v113, 0xffff0000, v12
	v_lshlrev_b32_e32 v114, 16, v13
	v_and_b32_e32 v115, 0xffff0000, v13
	v_lshlrev_b32_e32 v116, 16, v14
	v_and_b32_e32 v117, 0xffff0000, v14
	v_lshlrev_b32_e32 v118, 16, v15
	v_and_b32_e32 v119, 0xffff0000, v15
	v_mul_f32_e32 v26, v88, v88
	v_mul_f32_e32 v27, v96, v96
	v_mul_f32_e32 v29, v104, v104
	v_mul_f32_e32 v31, v112, v112
	v_fmac_f32_e32 v26, v89, v89
	v_fmac_f32_e32 v27, v97, v97
	v_fmac_f32_e32 v29, v105, v105
	v_fmac_f32_e32 v31, v113, v113
	v_fmac_f32_e32 v26, v90, v90
	v_fmac_f32_e32 v27, v98, v98
	v_fmac_f32_e32 v29, v106, v106
	v_fmac_f32_e32 v31, v114, v114
	v_fmac_f32_e32 v26, v91, v91
	v_fmac_f32_e32 v27, v99, v99
	v_fmac_f32_e32 v29, v107, v107
	v_fmac_f32_e32 v31, v115, v115
	v_fmac_f32_e32 v26, v92, v92
	v_fmac_f32_e32 v27, v100, v100
	v_fmac_f32_e32 v29, v108, v108
	v_fmac_f32_e32 v31, v116, v116
	v_fmac_f32_e32 v26, v93, v93
	v_fmac_f32_e32 v27, v101, v101
	v_fmac_f32_e32 v29, v109, v109
	v_fmac_f32_e32 v31, v117, v117
	v_fmac_f32_e32 v26, v94, v94
	v_fmac_f32_e32 v27, v102, v102
	v_fmac_f32_e32 v29, v110, v110
	v_fmac_f32_e32 v31, v118, v118
	v_fmac_f32_e32 v26, v95, v95
	v_fmac_f32_e32 v27, v103, v103
	v_fmac_f32_e32 v29, v111, v111
	v_fmac_f32_e32 v31, v119, v119
	v_add_f32_e32 v26, v26, v27
	v_add_f32_e32 v29, v29, v31
	v_add_f32_e32 v22, v26, v29
	s_nop 1
	v_add_f32_dpp v22, v22, v22 quad_perm:[1,0,3,2] row_mask:0xf bank_mask:0xf
	s_nop 1
	v_add_f32_dpp v22, v22, v22 quad_perm:[2,3,0,1] row_mask:0xf bank_mask:0xf
	s_nop 1
	v_add_f32_dpp v22, v22, v22 row_half_mirror row_mask:0xf bank_mask:0xf
	s_nop 1
	v_add_f32_dpp v22, v22, v22 row_mirror row_mask:0xf bank_mask:0xf
	ds_swizzle_b32 v24, v22 offset:0x401f
	s_waitcnt lgkmcnt(0)
	v_add_f32_e32 v22, v22, v24
	v_mov_b32_e32 v24, v22
	s_nop 1
	v_permlane32_swap_b32_e32 v22, v24
	v_add_f32_e32 v22, v22, v24
	v_fmamk_f32 v22, v22, 0x3a000000, v21
	v_rsq_f32_e32 v22, v22
	s_nop 0
	v_mul_f32_e32 v22, 0.5, v22
	v_mul_f32_e32 v88, v22, v88
	v_mul_f32_e32 v89, v22, v89
	v_mul_f32_e32 v90, v22, v90
	v_mul_f32_e32 v91, v22, v91
	v_mul_f32_e32 v92, v22, v92
	v_mul_f32_e32 v93, v22, v93
	v_mul_f32_e32 v94, v22, v94
	v_mul_f32_e32 v95, v22, v95
	v_mul_f32_e32 v96, v22, v96
	v_mul_f32_e32 v97, v22, v97
	v_mul_f32_e32 v98, v22, v98
	v_mul_f32_e32 v99, v22, v99
	v_mul_f32_e32 v100, v22, v100
	v_mul_f32_e32 v101, v22, v101
	v_mul_f32_e32 v102, v22, v102
	v_mul_f32_e32 v103, v22, v103
	v_mul_f32_e32 v104, v22, v104
	v_mul_f32_e32 v105, v22, v105
	v_mul_f32_e32 v106, v22, v106
	v_mul_f32_e32 v107, v22, v107
	v_mul_f32_e32 v108, v22, v108
	v_mul_f32_e32 v109, v22, v109
	v_mul_f32_e32 v110, v22, v110
	v_mul_f32_e32 v111, v22, v111
	v_mul_f32_e32 v112, v22, v112
	v_mul_f32_e32 v113, v22, v113
	v_mul_f32_e32 v114, v22, v114
	v_mul_f32_e32 v115, v22, v115
	v_mul_f32_e32 v116, v22, v116
	v_mul_f32_e32 v117, v22, v117
	v_mul_f32_e32 v118, v22, v118
	v_mul_f32_e32 v119, v22, v119
	s_waitcnt vmcnt(0)
; __device__ __forceinline__ u32x4 pack8(f32x4 a, f32x4 b) { u32x4 o; o.x = pk2(a[0], a[1]); o.y = pk2(a[2], a[3]); o.z = pk2(b[0], b[1]); o.w = pk2(b[2], b[3]); return o; }
; __device__ __forceinline__ void rowwise_row(const bf16_t* frow, const float* hin, float coef, const float* gpost, float* hout, const float* gpre, bf16_t* xn, int lane) {
;     ...
; #pragma unroll
;     for (int j = 0; j < 4; ++j)
; #pragma unroll
;         for (int q = 0; q < 2; ++q) { const int c = 512 * j + 8 * lane + 4 * q; const f32x4 hv = *(const f32x4*)(hin + c), gp = *(const f32x4*)(gpost + c);
;             h[j][q] = hv + f[j][q] * rs * gp; *(f32x4*)(hout + c) = h[j][q];
; #pragma unroll
;             for (int i = 0; i < 4; ++i) s2 += h[j][q][i] * h[j][q][i]; }
;     if (xn) { const float r2 = __frsqrt_rn(wave_sum(s2) * (1.f / DM) + EPS);
; #pragma unroll
;         for (int j = 0; j < 4; ++j) { const int c = 512 * j + 8 * lane; const f32x4 g0 = *(const f32x4*)(gpre + c), g1 = *(const f32x4*)(gpre + c + 4);
;             *(u32x4*)(xn + c) = pack8(h[j][0] * r2 * g0, h[j][1] * r2 * g1); } }
; __global__ void __launch_bounds__(NTHREADS, 2) fwd_kernel(Params P) {
;     ...
;     for (int m = gw; m < MTOK; m += NGW) rowwise_row(FB + (size_t)m * DM, x + (size_t)m * DM, 0.5f, P.in[5], out + (size_t)m * DM, P.in[6], XN + (size_t)m * DM, lane);
	v_fma_f32 v56, v120, v88, v56
	v_fma_f32 v57, v121, v89, v57
	v_fma_f32 v58, v122, v90, v58
	v_fma_f32 v59, v123, v91, v59
	v_fma_f32 v60, v124, v92, v60
	v_fma_f32 v61, v125, v93, v61
	v_fma_f32 v62, v126, v94, v62
	v_fma_f32 v63, v127, v95, v63
	v_fma_f32 v64, v128, v96, v64
	v_fma_f32 v65, v129, v97, v65
	v_fma_f32 v66, v130, v98, v66
	v_fma_f32 v67, v131, v99, v67
	v_fma_f32 v68, v132, v100, v68
	v_fma_f32 v69, v133, v101, v69
	v_fma_f32 v70, v134, v102, v70
	v_fma_f32 v71, v135, v103, v71
	v_fma_f32 v72, v136, v104, v72
	v_fma_f32 v73, v137, v105, v73
	v_fma_f32 v74, v138, v106, v74
	v_fma_f32 v75, v139, v107, v75
	v_fma_f32 v76, v140, v108, v76
	v_fma_f32 v77, v141, v109, v77
	v_fma_f32 v78, v142, v110, v78
	v_fma_f32 v79, v143, v111, v79
	v_fma_f32 v80, v144, v112, v80
	v_fma_f32 v81, v145, v113, v81
	v_fma_f32 v82, v146, v114, v82
	v_fma_f32 v83, v147, v115, v83
	v_fma_f32 v84, v148, v116, v84
	v_fma_f32 v85, v149, v117, v85
	v_fma_f32 v86, v150, v118, v86
	v_fma_f32 v87, v151, v119, v87
	global_store_dwordx4 v17, v[56:59], s[28:29] offset:0 nt
	global_store_dwordx4 v17, v[60:63], s[28:29] offset:16 nt
	global_store_dwordx4 v17, v[64:67], s[28:29] offset:2048 nt
	global_store_dwordx4 v17, v[68:71], s[28:29] offset:2064 nt
	global_store_dwordx4 v18, v[72:75], s[28:29] offset:0 nt
	global_store_dwordx4 v18, v[76:79], s[28:29] offset:16 nt
	global_store_dwordx4 v18, v[80:83], s[28:29] offset:2048 nt
	global_store_dwordx4 v18, v[84:87], s[28:29] offset:2064 nt
	v_mul_f32_e32 v26, v56, v56
	v_mul_f32_e32 v27, v64, v64
	v_mul_f32_e32 v29, v72, v72
	v_mul_f32_e32 v31, v80, v80
	v_fmac_f32_e32 v26, v57, v57
	v_fmac_f32_e32 v27, v65, v65
	v_fmac_f32_e32 v29, v73, v73
	v_fmac_f32_e32 v31, v81, v81
	v_fmac_f32_e32 v26, v58, v58
	v_fmac_f32_e32 v27, v66, v66
	v_fmac_f32_e32 v29, v74, v74
	v_fmac_f32_e32 v31, v82, v82
	v_fmac_f32_e32 v26, v59, v59
	v_fmac_f32_e32 v27, v67, v67
	v_fmac_f32_e32 v29, v75, v75
	v_fmac_f32_e32 v31, v83, v83
	v_fmac_f32_e32 v26, v60, v60
	v_fmac_f32_e32 v27, v68, v68
	v_fmac_f32_e32 v29, v76, v76
	v_fmac_f32_e32 v31, v84, v84
	v_fmac_f32_e32 v26, v61, v61
	v_fmac_f32_e32 v27, v69, v69
	v_fmac_f32_e32 v29, v77, v77
	v_fmac_f32_e32 v31, v85, v85
	v_fmac_f32_e32 v26, v62, v62
	v_fmac_f32_e32 v27, v70, v70
	v_fmac_f32_e32 v29, v78, v78
	v_fmac_f32_e32 v31, v86, v86
	v_fmac_f32_e32 v26, v63, v63
	v_fmac_f32_e32 v27, v71, v71
	v_fmac_f32_e32 v29, v79, v79
	v_fmac_f32_e32 v31, v87, v87
	v_add_f32_e32 v26, v26, v27
	v_add_f32_e32 v29, v29, v31
	v_add_f32_e32 v23, v26, v29
	s_nop 1
	v_add_f32_dpp v23, v23, v23 quad_perm:[1,0,3,2] row_mask:0xf bank_mask:0xf
	s_nop 1
	v_add_f32_dpp v23, v23, v23 quad_perm:[2,3,0,1] row_mask:0xf bank_mask:0xf
	s_nop 1
	v_add_f32_dpp v23, v23, v23 row_half_mirror row_mask:0xf bank_mask:0xf
	s_nop 1
	v_add_f32_dpp v23, v23, v23 row_mirror row_mask:0xf bank_mask:0xf
	ds_swizzle_b32 v24, v23 offset:0x401f
	s_waitcnt lgkmcnt(0)
	v_add_f32_e32 v23, v23, v24
	v_mov_b32_e32 v24, v23
	s_nop 1
	v_permlane32_swap_b32_e32 v23, v24
	v_add_f32_e32 v23, v23, v24
	v_fmamk_f32 v23, v23, 0x3a000000, v21
	v_rsq_f32_e32 v23, v23
	s_nop 0
	v_mul_f32_e32 v88, v56, v23
	v_mul_f32_e32 v89, v57, v23
	v_mul_f32_e32 v90, v58, v23
	v_mul_f32_e32 v91, v59, v23
	v_mul_f32_e32 v92, v60, v23
	v_mul_f32_e32 v93, v61, v23
	v_mul_f32_e32 v94, v62, v23
	v_mul_f32_e32 v95, v63, v23
	v_mul_f32_e32 v96, v64, v23
	v_mul_f32_e32 v97, v65, v23
	v_mul_f32_e32 v98, v66, v23
	v_mul_f32_e32 v99, v67, v23
	v_mul_f32_e32 v100, v68, v23
	v_mul_f32_e32 v101, v69, v23
	v_mul_f32_e32 v102, v70, v23
	v_mul_f32_e32 v103, v71, v23
	v_mul_f32_e32 v104, v72, v23
	v_mul_f32_e32 v105, v73, v23
	v_mul_f32_e32 v106, v74, v23
	v_mul_f32_e32 v107, v75, v23
	v_mul_f32_e32 v108, v76, v23
	v_mul_f32_e32 v109, v77, v23
	v_mul_f32_e32 v110, v78, v23
	v_mul_f32_e32 v111, v79, v23
	v_mul_f32_e32 v112, v80, v23
	v_mul_f32_e32 v113, v81, v23
	v_mul_f32_e32 v114, v82, v23
	v_mul_f32_e32 v115, v83, v23
	v_mul_f32_e32 v116, v84, v23
	v_mul_f32_e32 v117, v85, v23
	v_mul_f32_e32 v118, v86, v23
	v_mul_f32_e32 v119, v87, v23
	v_mul_f32_e32 v88, v152, v88
	v_mul_f32_e32 v89, v153, v89
	v_mul_f32_e32 v90, v154, v90
	v_mul_f32_e32 v91, v155, v91
	v_mul_f32_e32 v92, v156, v92
	v_mul_f32_e32 v93, v157, v93
	v_mul_f32_e32 v94, v158, v94
	v_mul_f32_e32 v95, v159, v95
	v_mul_f32_e32 v96, v160, v96
	v_mul_f32_e32 v97, v161, v97
	v_mul_f32_e32 v98, v162, v98
	v_mul_f32_e32 v99, v163, v99
	v_mul_f32_e32 v100, v164, v100
	v_mul_f32_e32 v101, v165, v101
	v_mul_f32_e32 v102, v166, v102
	v_mul_f32_e32 v103, v167, v103
	v_mul_f32_e32 v104, v168, v104
	v_mul_f32_e32 v105, v169, v105
	v_mul_f32_e32 v106, v170, v106
	v_mul_f32_e32 v107, v171, v107
	v_mul_f32_e32 v108, v172, v108
	v_mul_f32_e32 v109, v173, v109
	v_mul_f32_e32 v110, v174, v110
	v_mul_f32_e32 v111, v175, v111
	v_mul_f32_e32 v112, v176, v112
	v_mul_f32_e32 v113, v177, v113
	v_mul_f32_e32 v114, v178, v114
	v_mul_f32_e32 v115, v179, v115
	v_mul_f32_e32 v116, v188, v116
	v_mul_f32_e32 v117, v189, v117
	v_mul_f32_e32 v118, v190, v118
	v_mul_f32_e32 v119, v191, v119
	v_cvt_pk_bf16_f32 v0, v88, v89
	v_cvt_pk_bf16_f32 v1, v90, v91
	v_cvt_pk_bf16_f32 v2, v92, v93
	v_cvt_pk_bf16_f32 v3, v94, v95
	v_cvt_pk_bf16_f32 v4, v96, v97
	v_cvt_pk_bf16_f32 v5, v98, v99
	v_cvt_pk_bf16_f32 v6, v100, v101
	v_cvt_pk_bf16_f32 v7, v102, v103
	v_cvt_pk_bf16_f32 v8, v104, v105
	v_cvt_pk_bf16_f32 v9, v106, v107
	v_cvt_pk_bf16_f32 v10, v108, v109
	v_cvt_pk_bf16_f32 v11, v110, v111
	v_cvt_pk_bf16_f32 v12, v112, v113
	v_cvt_pk_bf16_f32 v13, v114, v115
	v_cvt_pk_bf16_f32 v14, v116, v117
	v_cvt_pk_bf16_f32 v15, v118, v119
	global_store_dwordx4 v16, v[0:3], s[6:7] offset:0
	global_store_dwordx4 v16, v[4:7], s[6:7] offset:1024
	global_store_dwordx4 v16, v[8:11], s[6:7] offset:2048
	global_store_dwordx4 v16, v[12:15], s[6:7] offset:3072
	s_lshl_b32 s1, s26, 12
	s_nop 0
	v_add_u32_e32 v16, s1, v16
	s_lshl_b32 s1, s26, 13
	v_add_u32_e32 v17, s1, v17
	v_add_u32_e32 v18, s1, v18
	s_add_i32 s10, s10, s26
	s_cmpk_gt_i32 s10, 0x7fff
	s_cbranch_scc0 .Lrow_top_p3
	s_nop 4

; __device__ __forceinline__ void unpack8(u32x4 v, f32x4& a, f32x4& b) { a[0] = bflo(v.x); a[1] = bfhi(v.x); a[2] = bflo(v.y); a[3] = bfhi(v.y); b[0] = bflo(v.z); b[1] = bfhi(v.z); b[2] = bflo(v.w); b[3] = bfhi(v.w); }
; __device__ __forceinline__ void rowwise_row(const bf16_t* frow, const float* hin, float coef, const float* gpost, float* hout, const float* gpre, bf16_t* xn, int lane) {
;     f32x4 f[4][2], h[4][2]; float ss = 0.f;
; #pragma unroll
;     for (int j = 0; j < 4; ++j) { unpack8(*(const u32x4*)(frow + 512 * j + 8 * lane), f[j][0], f[j][1]);
; #pragma unroll
;         for (int i = 0; i < 4; ++i) ss += f[j][0][i] * f[j][0][i] + f[j][1][i] * f[j][1][i]; }
;     const float rs = coef * __frsqrt_rn(wave_sum(ss) * (1.f / DM) + EPS); float s2 = 0.f;
.Lrow_top_p11:
	global_load_dwordx4 v[0:3], v16, s[4:5] offset:0 nt
	global_load_dwordx4 v[4:7], v16, s[4:5] offset:1024 nt
	global_load_dwordx4 v[8:11], v16, s[4:5] offset:2048 nt
	global_load_dwordx4 v[12:15], v16, s[4:5] offset:3072 nt
	global_load_dwordx4 v[56:59], v17, s[28:29] offset:0 nt
	global_load_dwordx4 v[60:63], v17, s[28:29] offset:16 nt
	global_load_dwordx4 v[64:67], v17, s[28:29] offset:2048 nt
	global_load_dwordx4 v[68:71], v17, s[28:29] offset:2064 nt
	global_load_dwordx4 v[72:75], v18, s[28:29] offset:0 nt
	global_load_dwordx4 v[76:79], v18, s[28:29] offset:16 nt
	global_load_dwordx4 v[80:83], v18, s[28:29] offset:2048 nt
	global_load_dwordx4 v[84:87], v18, s[28:29] offset:2064 nt
	s_waitcnt vmcnt(8)
	v_lshlrev_b32_e32 v88, 16, v0
	v_and_b32_e32 v89, 0xffff0000, v0
	v_lshlrev_b32_e32 v90, 16, v1
	v_and_b32_e32 v91, 0xffff0000, v1
	v_lshlrev_b32_e32 v92, 16, v2
	v_and_b32_e32 v93, 0xffff0000, v2
	v_lshlrev_b32_e32 v94, 16, v3
	v_and_b32_e32 v95, 0xffff0000, v3
	v_lshlrev_b32_e32 v96, 16, v4
	v_and_b32_e32 v97, 0xffff0000, v4
	v_lshlrev_b32_e32 v98, 16, v5
	v_and_b32_e32 v99, 0xffff0000, v5
	v_lshlrev_b32_e32 v100, 16, v6
	v_and_b32_e32 v101, 0xffff0000, v6
	v_lshlrev_b32_e32 v102, 16, v7
	v_and_b32_e32 v103, 0xffff0000, v7
	v_lshlrev_b32_e32 v104, 16, v8
	v_and_b32_e32 v105, 0xffff0000, v8
	v_lshlrev_b32_e32 v106, 16, v9
	v_and_b32_e32 v107, 0xffff0000, v9
	v_lshlrev_b32_e32 v108, 16, v10
	v_and_b32_e32 v109, 0xffff0000, v10
	v_lshlrev_b32_e32 v110, 16, v11
	v_and_b32_e32 v111, 0xffff0000, v11
	v_lshlrev_b32_e32 v112, 16, v12
	v_and_b32_e32 v113, 0xffff0000, v12
	v_lshlrev_b32_e32 v114, 16, v13
	v_and_b32_e32 v115, 0xffff0000, v13
	v_lshlrev_b32_e32 v116, 16, v14
	v_and_b32_e32 v117, 0xffff0000, v14
	v_lshlrev_b32_e32 v118, 16, v15
	v_and_b32_e32 v119, 0xffff0000, v15
	v_mul_f32_e32 v26, v88, v88
	v_mul_f32_e32 v27, v96, v96
	v_mul_f32_e32 v29, v104, v104
	v_mul_f32_e32 v31, v112, v112
	v_fmac_f32_e32 v26, v89, v89
	v_fmac_f32_e32 v27, v97, v97
	v_fmac_f32_e32 v29, v105, v105
	v_fmac_f32_e32 v31, v113, v113
	v_fmac_f32_e32 v26, v90, v90
	v_fmac_f32_e32 v27, v98, v98
	v_fmac_f32_e32 v29, v106, v106
	v_fmac_f32_e32 v31, v114, v114
	v_fmac_f32_e32 v26, v91, v91
	v_fmac_f32_e32 v27, v99, v99
	v_fmac_f32_e32 v29, v107, v107
	v_fmac_f32_e32 v31, v115, v115
	v_fmac_f32_e32 v26, v92, v92
	v_fmac_f32_e32 v27, v100, v100
	v_fmac_f32_e32 v29, v108, v108
	v_fmac_f32_e32 v31, v116, v116
	v_fmac_f32_e32 v26, v93, v93
	v_fmac_f32_e32 v27, v101, v101
	v_fmac_f32_e32 v29, v109, v109
	v_fmac_f32_e32 v31, v117, v117
	v_fmac_f32_e32 v26, v94, v94
	v_fmac_f32_e32 v27, v102, v102
	v_fmac_f32_e32 v29, v110, v110
	v_fmac_f32_e32 v31, v118, v118
	v_fmac_f32_e32 v26, v95, v95
	v_fmac_f32_e32 v27, v103, v103
	v_fmac_f32_e32 v29, v111, v111
	v_fmac_f32_e32 v31, v119, v119
	v_add_f32_e32 v26, v26, v27
	v_add_f32_e32 v29, v29, v31
	v_add_f32_e32 v22, v26, v29
	s_nop 1
	v_add_f32_dpp v22, v22, v22 quad_perm:[1,0,3,2] row_mask:0xf bank_mask:0xf
	s_nop 1
	v_add_f32_dpp v22, v22, v22 quad_perm:[2,3,0,1] row_mask:0xf bank_mask:0xf
	s_nop 1
	v_add_f32_dpp v22, v22, v22 row_half_mirror row_mask:0xf bank_mask:0xf
	s_nop 1
	v_add_f32_dpp v22, v22, v22 row_mirror row_mask:0xf bank_mask:0xf
	ds_swizzle_b32 v24, v22 offset:0x401f
	s_waitcnt lgkmcnt(0)
	v_add_f32_e32 v22, v22, v24
	v_mov_b32_e32 v24, v22
	s_nop 1
	v_permlane32_swap_b32_e32 v22, v24
	v_add_f32_e32 v22, v22, v24
	v_fmamk_f32 v22, v22, 0x3a000000, v21
	v_rsq_f32_e32 v22, v22
	s_nop 0
	v_mul_f32_e32 v88, v22, v88
	v_mul_f32_e32 v89, v22, v89
	v_mul_f32_e32 v90, v22, v90
	v_mul_f32_e32 v91, v22, v91
	v_mul_f32_e32 v92, v22, v92
	v_mul_f32_e32 v93, v22, v93
	v_mul_f32_e32 v94, v22, v94
	v_mul_f32_e32 v95, v22, v95
	v_mul_f32_e32 v96, v22, v96
	v_mul_f32_e32 v97, v22, v97
	v_mul_f32_e32 v98, v22, v98
	v_mul_f32_e32 v99, v22, v99
	v_mul_f32_e32 v100, v22, v100
	v_mul_f32_e32 v101, v22, v101
	v_mul_f32_e32 v102, v22, v102
	v_mul_f32_e32 v103, v22, v103
	v_mul_f32_e32 v104, v22, v104
	v_mul_f32_e32 v105, v22, v105
	v_mul_f32_e32 v106, v22, v106
	v_mul_f32_e32 v107, v22, v107
	v_mul_f32_e32 v108, v22, v108
	v_mul_f32_e32 v109, v22, v109
	v_mul_f32_e32 v110, v22, v110
	v_mul_f32_e32 v111, v22, v111
	v_mul_f32_e32 v112, v22, v112
	v_mul_f32_e32 v113, v22, v113
	v_mul_f32_e32 v114, v22, v114
	v_mul_f32_e32 v115, v22, v115
	v_mul_f32_e32 v116, v22, v116
	v_mul_f32_e32 v117, v22, v117
	v_mul_f32_e32 v118, v22, v118
	v_mul_f32_e32 v119, v22, v119
	s_waitcnt vmcnt(0)
; __device__ __forceinline__ u32x4 pack8(f32x4 a, f32x4 b) { u32x4 o; o.x = pk2(a[0], a[1]); o.y = pk2(a[2], a[3]); o.z = pk2(b[0], b[1]); o.w = pk2(b[2], b[3]); return o; }
; __device__ __forceinline__ void rowwise_row(const bf16_t* frow, const float* hin, float coef, const float* gpost, float* hout, const float* gpre, bf16_t* xn, int lane) {
;     ...
; #pragma unroll
;     for (int j = 0; j < 4; ++j)
; #pragma unroll
;         for (int q = 0; q < 2; ++q) { const int c = 512 * j + 8 * lane + 4 * q; const f32x4 hv = *(const f32x4*)(hin + c), gp = *(const f32x4*)(gpost + c);
;             h[j][q] = hv + f[j][q] * rs * gp; *(f32x4*)(hout + c) = h[j][q];
; #pragma unroll
;             for (int i = 0; i < 4; ++i) s2 += h[j][q][i] * h[j][q][i]; }
;     if (xn) { const float r2 = __frsqrt_rn(wave_sum(s2) * (1.f / DM) + EPS);
; #pragma unroll
;         for (int j = 0; j < 4; ++j) { const int c = 512 * j + 8 * lane; const f32x4 g0 = *(const f32x4*)(gpre + c), g1 = *(const f32x4*)(gpre + c + 4);
;             *(u32x4*)(xn + c) = pack8(h[j][0] * r2 * g0, h[j][1] * r2 * g1); } }
; __global__ void __launch_bounds__(NTHREADS, 2) fwd_kernel(Params P) {
;     ...
;     for (int m = gw; m < MTOK; m += NGW) rowwise_row(MIXED + (size_t)m * DM, out + (size_t)m * DM, 1.0f, P.in[25], out + (size_t)m * DM, P.in[26], XN + (size_t)m * DM, lane);
	v_fma_f32 v56, v120, v88, v56
	v_fma_f32 v57, v121, v89, v57
	v_fma_f32 v58, v122, v90, v58
	v_fma_f32 v59, v123, v91, v59
	v_fma_f32 v60, v124, v92, v60
	v_fma_f32 v61, v125, v93, v61
	v_fma_f32 v62, v126, v94, v62
	v_fma_f32 v63, v127, v95, v63
	v_fma_f32 v64, v128, v96, v64
	v_fma_f32 v65, v129, v97, v65
	v_fma_f32 v66, v130, v98, v66
	v_fma_f32 v67, v131, v99, v67
	v_fma_f32 v68, v132, v100, v68
	v_fma_f32 v69, v133, v101, v69
	v_fma_f32 v70, v134, v102, v70
	v_fma_f32 v71, v135, v103, v71
	v_fma_f32 v72, v136, v104, v72
	v_fma_f32 v73, v137, v105, v73
	v_fma_f32 v74, v138, v106, v74
	v_fma_f32 v75, v139, v107, v75
	v_fma_f32 v76, v140, v108, v76
	v_fma_f32 v77, v141, v109, v77
	v_fma_f32 v78, v142, v110, v78
	v_fma_f32 v79, v143, v111, v79
	v_fma_f32 v80, v144, v112, v80
	v_fma_f32 v81, v145, v113, v81
	v_fma_f32 v82, v146, v114, v82
	v_fma_f32 v83, v147, v115, v83
	v_fma_f32 v84, v148, v116, v84
	v_fma_f32 v85, v149, v117, v85
	v_fma_f32 v86, v150, v118, v86
	v_fma_f32 v87, v151, v119, v87
	global_store_dwordx4 v17, v[56:59], s[28:29] offset:0 nt
	global_store_dwordx4 v17, v[60:63], s[28:29] offset:16 nt
	global_store_dwordx4 v17, v[64:67], s[28:29] offset:2048 nt
	global_store_dwordx4 v17, v[68:71], s[28:29] offset:2064 nt
	global_store_dwordx4 v18, v[72:75], s[28:29] offset:0 nt
	global_store_dwordx4 v18, v[76:79], s[28:29] offset:16 nt
	global_store_dwordx4 v18, v[80:83], s[28:29] offset:2048 nt
	global_store_dwordx4 v18, v[84:87], s[28:29] offset:2064 nt
	v_mul_f32_e32 v26, v56, v56
	v_mul_f32_e32 v27, v64, v64
	v_mul_f32_e32 v29, v72, v72
	v_mul_f32_e32 v31, v80, v80
	v_fmac_f32_e32 v26, v57, v57
	v_fmac_f32_e32 v27, v65, v65
	v_fmac_f32_e32 v29, v73, v73
	v_fmac_f32_e32 v31, v81, v81
	v_fmac_f32_e32 v26, v58, v58
	v_fmac_f32_e32 v27, v66, v66
	v_fmac_f32_e32 v29, v74, v74
	v_fmac_f32_e32 v31, v82, v82
	v_fmac_f32_e32 v26, v59, v59
	v_fmac_f32_e32 v27, v67, v67
	v_fmac_f32_e32 v29, v75, v75
	v_fmac_f32_e32 v31, v83, v83
	v_fmac_f32_e32 v26, v60, v60
	v_fmac_f32_e32 v27, v68, v68
	v_fmac_f32_e32 v29, v76, v76
	v_fmac_f32_e32 v31, v84, v84
	v_fmac_f32_e32 v26, v61, v61
	v_fmac_f32_e32 v27, v69, v69
	v_fmac_f32_e32 v29, v77, v77
	v_fmac_f32_e32 v31, v85, v85
	v_fmac_f32_e32 v26, v62, v62
	v_fmac_f32_e32 v27, v70, v70
	v_fmac_f32_e32 v29, v78, v78
	v_fmac_f32_e32 v31, v86, v86
	v_fmac_f32_e32 v26, v63, v63
	v_fmac_f32_e32 v27, v71, v71
	v_fmac_f32_e32 v29, v79, v79
	v_fmac_f32_e32 v31, v87, v87
	v_add_f32_e32 v26, v26, v27
	v_add_f32_e32 v29, v29, v31
	v_add_f32_e32 v23, v26, v29
	s_nop 1
	v_add_f32_dpp v23, v23, v23 quad_perm:[1,0,3,2] row_mask:0xf bank_mask:0xf
	s_nop 1
	v_add_f32_dpp v23, v23, v23 quad_perm:[2,3,0,1] row_mask:0xf bank_mask:0xf
	s_nop 1
	v_add_f32_dpp v23, v23, v23 row_half_mirror row_mask:0xf bank_mask:0xf
	s_nop 1
	v_add_f32_dpp v23, v23, v23 row_mirror row_mask:0xf bank_mask:0xf
	ds_swizzle_b32 v24, v23 offset:0x401f
	s_waitcnt lgkmcnt(0)
	v_add_f32_e32 v23, v23, v24
	v_mov_b32_e32 v24, v23
	s_nop 1
	v_permlane32_swap_b32_e32 v23, v24
	v_add_f32_e32 v23, v23, v24
	v_fmamk_f32 v23, v23, 0x3a000000, v21
	v_rsq_f32_e32 v23, v23
	s_nop 0
	v_mul_f32_e32 v88, v56, v23
	v_mul_f32_e32 v89, v57, v23
	v_mul_f32_e32 v90, v58, v23
	v_mul_f32_e32 v91, v59, v23
	v_mul_f32_e32 v92, v60, v23
	v_mul_f32_e32 v93, v61, v23
	v_mul_f32_e32 v94, v62, v23
	v_mul_f32_e32 v95, v63, v23
	v_mul_f32_e32 v96, v64, v23
	v_mul_f32_e32 v97, v65, v23
	v_mul_f32_e32 v98, v66, v23
	v_mul_f32_e32 v99, v67, v23
	v_mul_f32_e32 v100, v68, v23
	v_mul_f32_e32 v101, v69, v23
	v_mul_f32_e32 v102, v70, v23
	v_mul_f32_e32 v103, v71, v23
	v_mul_f32_e32 v104, v72, v23
	v_mul_f32_e32 v105, v73, v23
	v_mul_f32_e32 v106, v74, v23
	v_mul_f32_e32 v107, v75, v23
	v_mul_f32_e32 v108, v76, v23
	v_mul_f32_e32 v109, v77, v23
	v_mul_f32_e32 v110, v78, v23
	v_mul_f32_e32 v111, v79, v23
	v_mul_f32_e32 v112, v80, v23
	v_mul_f32_e32 v113, v81, v23
	v_mul_f32_e32 v114, v82, v23
	v_mul_f32_e32 v115, v83, v23
	v_mul_f32_e32 v116, v84, v23
	v_mul_f32_e32 v117, v85, v23
	v_mul_f32_e32 v118, v86, v23
	v_mul_f32_e32 v119, v87, v23
	v_mul_f32_e32 v88, v152, v88
	v_mul_f32_e32 v89, v153, v89
	v_mul_f32_e32 v90, v154, v90
	v_mul_f32_e32 v91, v155, v91
	v_mul_f32_e32 v92, v156, v92
	v_mul_f32_e32 v93, v157, v93
	v_mul_f32_e32 v94, v158, v94
	v_mul_f32_e32 v95, v159, v95
	v_mul_f32_e32 v96, v160, v96
	v_mul_f32_e32 v97, v161, v97
	v_mul_f32_e32 v98, v162, v98
	v_mul_f32_e32 v99, v163, v99
	v_mul_f32_e32 v100, v164, v100
	v_mul_f32_e32 v101, v165, v101
	v_mul_f32_e32 v102, v166, v102
	v_mul_f32_e32 v103, v167, v103
	v_mul_f32_e32 v104, v168, v104
	v_mul_f32_e32 v105, v169, v105
	v_mul_f32_e32 v106, v170, v106
	v_mul_f32_e32 v107, v171, v107
	v_mul_f32_e32 v108, v172, v108
	v_mul_f32_e32 v109, v173, v109
	v_mul_f32_e32 v110, v174, v110
	v_mul_f32_e32 v111, v175, v111
	v_mul_f32_e32 v112, v176, v112
	v_mul_f32_e32 v113, v177, v113
	v_mul_f32_e32 v114, v178, v114
	v_mul_f32_e32 v115, v179, v115
	v_mul_f32_e32 v116, v188, v116
	v_mul_f32_e32 v117, v189, v117
	v_mul_f32_e32 v118, v190, v118
	v_mul_f32_e32 v119, v191, v119
	v_cvt_pk_bf16_f32 v0, v88, v89
	v_cvt_pk_bf16_f32 v1, v90, v91
	v_cvt_pk_bf16_f32 v2, v92, v93
	v_cvt_pk_bf16_f32 v3, v94, v95
	v_cvt_pk_bf16_f32 v4, v96, v97
	v_cvt_pk_bf16_f32 v5, v98, v99
	v_cvt_pk_bf16_f32 v6, v100, v101
	v_cvt_pk_bf16_f32 v7, v102, v103
	v_cvt_pk_bf16_f32 v8, v104, v105
	v_cvt_pk_bf16_f32 v9, v106, v107
	v_cvt_pk_bf16_f32 v10, v108, v109
	v_cvt_pk_bf16_f32 v11, v110, v111
	v_cvt_pk_bf16_f32 v12, v112, v113
	v_cvt_pk_bf16_f32 v13, v114, v115
	v_cvt_pk_bf16_f32 v14, v116, v117
	v_cvt_pk_bf16_f32 v15, v118, v119
	global_store_dwordx4 v16, v[0:3], s[6:7] offset:0
	global_store_dwordx4 v16, v[4:7], s[6:7] offset:1024
	global_store_dwordx4 v16, v[8:11], s[6:7] offset:2048
	global_store_dwordx4 v16, v[12:15], s[6:7] offset:3072
	s_lshl_b32 s1, s26, 12
	s_nop 0
	v_add_u32_e32 v16, s1, v16
	s_lshl_b32 s1, s26, 13
	v_add_u32_e32 v17, s1, v17
	v_add_u32_e32 v18, s1, v18
	s_add_i32 s0, s0, s26
	s_cmpk_gt_i32 s0, 0x7fff
	s_cbranch_scc0 .Lrow_top_p11
	s_nop 4

; __device__ __forceinline__ void unpack8(u32x4 v, f32x4& a, f32x4& b) { a[0] = bflo(v.x); a[1] = bfhi(v.x); a[2] = bflo(v.y); a[3] = bfhi(v.y); b[0] = bflo(v.z); b[1] = bfhi(v.z); b[2] = bflo(v.w); b[3] = bfhi(v.w); }
; __device__ __forceinline__ void rowwise_row(const bf16_t* frow, const float* hin, float coef, const float* gpost, float* hout, const float* gpre, bf16_t* xn, int lane) {
;     f32x4 f[4][2], h[4][2]; float ss = 0.f;
; #pragma unroll
;     for (int j = 0; j < 4; ++j) { unpack8(*(const u32x4*)(frow + 512 * j + 8 * lane), f[j][0], f[j][1]);
; #pragma unroll
;         for (int i = 0; i < 4; ++i) ss += f[j][0][i] * f[j][0][i] + f[j][1][i] * f[j][1][i]; }
;     const float rs = coef * __frsqrt_rn(wave_sum(ss) * (1.f / DM) + EPS); float s2 = 0.f;
; #pragma unroll
;     for (int j = 0; j < 4; ++j)
; #pragma unroll
;         for (int q = 0; q < 2; ++q) { const int c = 512 * j + 8 * lane + 4 * q; const f32x4 hv = *(const f32x4*)(hin + c), gp = *(const f32x4*)(gpost + c);
;             h[j][q] = hv + f[j][q] * rs * gp; *(f32x4*)(hout + c) = h[j][q];
; #pragma unroll
;             for (int i = 0; i < 4; ++i) s2 += h[j][q][i] * h[j][q][i]; }
; __global__ void __launch_bounds__(NTHREADS, 2) fwd_kernel(Params P) {
;     ...
;     for (int m = gw; m < MTOK; m += NGW) rowwise_row(FB + (size_t)m * DM, out + (size_t)m * DM, 0.5f, P.in[30], out + (size_t)m * DM, nullptr, nullptr, lane);
.Lrow_top_p14:
	global_load_dwordx4 v[0:3], v16, s[4:5] offset:0 nt
	global_load_dwordx4 v[4:7], v16, s[4:5] offset:1024 nt
	global_load_dwordx4 v[8:11], v16, s[4:5] offset:2048 nt
	global_load_dwordx4 v[12:15], v16, s[4:5] offset:3072 nt
	global_load_dwordx4 v[56:59], v17, s[28:29] offset:0 nt
	global_load_dwordx4 v[60:63], v17, s[28:29] offset:16 nt
	global_load_dwordx4 v[64:67], v17, s[28:29] offset:2048 nt
	global_load_dwordx4 v[68:71], v17, s[28:29] offset:2064 nt
	global_load_dwordx4 v[72:75], v18, s[28:29] offset:0 nt
	global_load_dwordx4 v[76:79], v18, s[28:29] offset:16 nt
	global_load_dwordx4 v[80:83], v18, s[28:29] offset:2048 nt
	global_load_dwordx4 v[84:87], v18, s[28:29] offset:2064 nt
	s_waitcnt vmcnt(8)
	v_lshlrev_b32_e32 v88, 16, v0
	v_and_b32_e32 v89, 0xffff0000, v0
	v_lshlrev_b32_e32 v90, 16, v1
	v_and_b32_e32 v91, 0xffff0000, v1
	v_lshlrev_b32_e32 v92, 16, v2
	v_and_b32_e32 v93, 0xffff0000, v2
	v_lshlrev_b32_e32 v94, 16, v3
	v_and_b32_e32 v95, 0xffff0000, v3
	v_lshlrev_b32_e32 v96, 16, v4
	v_and_b32_e32 v97, 0xffff0000, v4
	v_lshlrev_b32_e32 v98, 16, v5
	v_and_b32_e32 v99, 0xffff0000, v5
	v_lshlrev_b32_e32 v100, 16, v6
	v_and_b32_e32 v101, 0xffff0000, v6
	v_lshlrev_b32_e32 v102, 16, v7
	v_and_b32_e32 v103, 0xffff0000, v7
	v_lshlrev_b32_e32 v104, 16, v8
	v_and_b32_e32 v105, 0xffff0000, v8
	v_lshlrev_b32_e32 v106, 16, v9
	v_and_b32_e32 v107, 0xffff0000, v9
	v_lshlrev_b32_e32 v108, 16, v10
	v_and_b32_e32 v109, 0xffff0000, v10
	v_lshlrev_b32_e32 v110, 16, v11
	v_and_b32_e32 v111, 0xffff0000, v11
	v_lshlrev_b32_e32 v112, 16, v12
	v_and_b32_e32 v113, 0xffff0000, v12
	v_lshlrev_b32_e32 v114, 16, v13
	v_and_b32_e32 v115, 0xffff0000, v13
	v_lshlrev_b32_e32 v116, 16, v14
	v_and_b32_e32 v117, 0xffff0000, v14
	v_lshlrev_b32_e32 v118, 16, v15
	v_and_b32_e32 v119, 0xffff0000, v15
	v_mul_f32_e32 v26, v88, v88
	v_mul_f32_e32 v27, v96, v96
	v_mul_f32_e32 v29, v104, v104
	v_mul_f32_e32 v31, v112, v112
	v_fmac_f32_e32 v26, v89, v89
	v_fmac_f32_e32 v27, v97, v97
	v_fmac_f32_e32 v29, v105, v105
	v_fmac_f32_e32 v31, v113, v113
	v_fmac_f32_e32 v26, v90, v90
	v_fmac_f32_e32 v27, v98, v98
	v_fmac_f32_e32 v29, v106, v106
	v_fmac_f32_e32 v31, v114, v114
	v_fmac_f32_e32 v26, v91, v91
	v_fmac_f32_e32 v27, v99, v99
	v_fmac_f32_e32 v29, v107, v107
	v_fmac_f32_e32 v31, v115, v115
	v_fmac_f32_e32 v26, v92, v92
	v_fmac_f32_e32 v27, v100, v100
	v_fmac_f32_e32 v29, v108, v108
	v_fmac_f32_e32 v31, v116, v116
	v_fmac_f32_e32 v26, v93, v93
	v_fmac_f32_e32 v27, v101, v101
	v_fmac_f32_e32 v29, v109, v109
	v_fmac_f32_e32 v31, v117, v117
	v_fmac_f32_e32 v26, v94, v94
	v_fmac_f32_e32 v27, v102, v102
	v_fmac_f32_e32 v29, v110, v110
	v_fmac_f32_e32 v31, v118, v118
	v_fmac_f32_e32 v26, v95, v95
	v_fmac_f32_e32 v27, v103, v103
	v_fmac_f32_e32 v29, v111, v111
	v_fmac_f32_e32 v31, v119, v119
	v_add_f32_e32 v26, v26, v27
	v_add_f32_e32 v29, v29, v31
	v_add_f32_e32 v22, v26, v29
	s_nop 1
	v_add_f32_dpp v22, v22, v22 quad_perm:[1,0,3,2] row_mask:0xf bank_mask:0xf
	s_nop 1
	v_add_f32_dpp v22, v22, v22 quad_perm:[2,3,0,1] row_mask:0xf bank_mask:0xf
	s_nop 1
	v_add_f32_dpp v22, v22, v22 row_half_mirror row_mask:0xf bank_mask:0xf
	s_nop 1
	v_add_f32_dpp v22, v22, v22 row_mirror row_mask:0xf bank_mask:0xf
	ds_swizzle_b32 v24, v22 offset:0x401f
	s_waitcnt lgkmcnt(0)
	v_add_f32_e32 v22, v22, v24
	v_mov_b32_e32 v24, v22
	s_nop 1
	v_permlane32_swap_b32_e32 v22, v24
	v_add_f32_e32 v22, v22, v24
	v_fmamk_f32 v22, v22, 0x3a000000, v21
	v_rsq_f32_e32 v22, v22
	s_nop 0
	v_mul_f32_e32 v22, 0.5, v22
	v_mul_f32_e32 v88, v22, v88
	v_mul_f32_e32 v89, v22, v89
	v_mul_f32_e32 v90, v22, v90
	v_mul_f32_e32 v91, v22, v91
	v_mul_f32_e32 v92, v22, v92
	v_mul_f32_e32 v93, v22, v93
	v_mul_f32_e32 v94, v22, v94
	v_mul_f32_e32 v95, v22, v95
	v_mul_f32_e32 v96, v22, v96
	v_mul_f32_e32 v97, v22, v97
	v_mul_f32_e32 v98, v22, v98
	v_mul_f32_e32 v99, v22, v99
	v_mul_f32_e32 v100, v22, v100
	v_mul_f32_e32 v101, v22, v101
	v_mul_f32_e32 v102, v22, v102
	v_mul_f32_e32 v103, v22, v103
	v_mul_f32_e32 v104, v22, v104
	v_mul_f32_e32 v105, v22, v105
	v_mul_f32_e32 v106, v22, v106
	v_mul_f32_e32 v107, v22, v107
	v_mul_f32_e32 v108, v22, v108
	v_mul_f32_e32 v109, v22, v109
	v_mul_f32_e32 v110, v22, v110
	v_mul_f32_e32 v111, v22, v111
	v_mul_f32_e32 v112, v22, v112
	v_mul_f32_e32 v113, v22, v113
	v_mul_f32_e32 v114, v22, v114
	v_mul_f32_e32 v115, v22, v115
	v_mul_f32_e32 v116, v22, v116
	v_mul_f32_e32 v117, v22, v117
	v_mul_f32_e32 v118, v22, v118
	v_mul_f32_e32 v119, v22, v119
	s_waitcnt vmcnt(0)
	v_fma_f32 v56, v120, v88, v56
	v_fma_f32 v57, v121, v89, v57
	v_fma_f32 v58, v122, v90, v58
	v_fma_f32 v59, v123, v91, v59
	v_fma_f32 v60, v124, v92, v60
	v_fma_f32 v61, v125, v93, v61
	v_fma_f32 v62, v126, v94, v62
	v_fma_f32 v63, v127, v95, v63
	v_fma_f32 v64, v128, v96, v64
	v_fma_f32 v65, v129, v97, v65
	v_fma_f32 v66, v130, v98, v66
	v_fma_f32 v67, v131, v99, v67
	v_fma_f32 v68, v132, v100, v68
	v_fma_f32 v69, v133, v101, v69
	v_fma_f32 v70, v134, v102, v70
	v_fma_f32 v71, v135, v103, v71
	v_fma_f32 v72, v136, v104, v72
	v_fma_f32 v73, v137, v105, v73
	v_fma_f32 v74, v138, v106, v74
	v_fma_f32 v75, v139, v107, v75
	v_fma_f32 v76, v140, v108, v76
	v_fma_f32 v77, v141, v109, v77
	v_fma_f32 v78, v142, v110, v78
	v_fma_f32 v79, v143, v111, v79
	v_fma_f32 v80, v144, v112, v80
	v_fma_f32 v81, v145, v113, v81
	v_fma_f32 v82, v146, v114, v82
	v_fma_f32 v83, v147, v115, v83
	v_fma_f32 v84, v148, v116, v84
	v_fma_f32 v85, v149, v117, v85
	v_fma_f32 v86, v150, v118, v86
	v_fma_f32 v87, v151, v119, v87
	global_store_dwordx4 v17, v[56:59], s[28:29] offset:0 nt
	global_store_dwordx4 v17, v[60:63], s[28:29] offset:16 nt
	global_store_dwordx4 v17, v[64:67], s[28:29] offset:2048 nt
	global_store_dwordx4 v17, v[68:71], s[28:29] offset:2064 nt
	global_store_dwordx4 v18, v[72:75], s[28:29] offset:0 nt
	global_store_dwordx4 v18, v[76:79], s[28:29] offset:16 nt
	global_store_dwordx4 v18, v[80:83], s[28:29] offset:2048 nt
	global_store_dwordx4 v18, v[84:87], s[28:29] offset:2064 nt
	s_lshl_b32 s1, s26, 12
	v_add_u32_e32 v16, s1, v16
	s_lshl_b32 s1, s26, 13
	v_add_u32_e32 v17, s1, v17
	v_add_u32_e32 v18, s1, v18
	s_add_i32 s0, s0, s26
	s_cmpk_gt_i32 s0, 0x7fff
	s_cbranch_scc0 .Lrow_top_p14
	s_nop 4
